# attention: next item's first K/V chunk prefetched by LDS-DMA during the last chunk (strategy 7.10), read back from LDS in the prologue; output image moved into the idle K/V area
# speedup vs baseline: 1.0002x; 1.0002x over previous
; __device__ __forceinline__ int tid_opaque(int wv) { return wv * 64 + lane_fresh(); }
; __device__ __forceinline__ unsigned cvt_pk_bf16(float lo, float hi) { unsigned r; asm("v_cvt_pk_bf16_f32 %0, %1, %2" : "=v"(r) : "v"(lo), "v"(hi)); return r; }
; __device__ __forceinline__ void attn_mfma(PP p, unsigned char* shm, int wv) {
;     const int tid = tid_opaque(wv);
;     const int lane = tid & 63, wave = wv, l31 = lane & 31, hl = lane >> 5;
;     const bf16_t* proj = (const bf16_t*)(p->ws + WS_PROJ);
;     bf16_t* att = (bf16_t*)(p->ws + WS_ATT);
;     const float L2E = 1.4426950408889634f;
;     const float SC2 = 0.125f * L2E;
;     for (int item = blockIdx.x; item < 512; item += gridDim.x) {
;         const int hk = item & 1, qb = (item >> 1) & 127, b = item >> 8;
;         const int g = wave >> 1, qh = wave & 1, hq = hk * 4 + g;
;         const int qrow0 = b * S + 128 * qb + 64 * qh;
;     ...
;         for (int qi = 0; qi < 2; ++qi) {
;             const float lt = lrun[qi] + __shfl_xor(lrun[qi], 32);
;             const float inv = 1.0f / lt;
;             bf16_t* orow = att + (size_t)(qrow0 + 32 * qi + l31) * 512 + hq * 64;
; #pragma unroll
;             for (int db = 0; db < 2; ++db)
; #pragma unroll
;                 for (int g4 = 0; g4 < 4; ++g4) {
;                     u32x2 w; w.x = cvt_pk_bf16(oacc[db][qi][4 * g4] * inv, oacc[db][qi][4 * g4 + 1] * inv); w.y = cvt_pk_bf16(oacc[db][qi][4 * g4 + 2] * inv, oacc[db][qi][4 * g4 + 3] * inv);
;                     *(u32x2*)(orow + 32 * db + 8 * g4 + 4 * hl) = w;
;                 }
;         }
.LBB0_453:
	s_cmpk_lt_i32 s2, 0x200
	s_mov_b64 s[4:5], s[0:1]
	s_cselect_b64 s[22:23], -1, 0
	s_cmpk_gt_i32 s2, 0x1ff
	s_cbranch_scc1 .LBB0_489
	s_mov_b32 s97, 0
	s_load_dwordx2 s[14:15], s[4:5], 0xd0
	s_load_dwordx2 s[8:9], s[4:5], 0x78
	v_mbcnt_lo_u32_b32 v1, s27, 0
	v_mbcnt_hi_u32_b32 v1, s27, v1
	v_mov_b32_e32 v0, 0
	s_waitcnt lgkmcnt(0)
	s_add_u32 s4, s14, 0x9c77000
	v_bfe_u32 v6, v1, 5, 1
	v_and_b32_e32 v8, 31, v1
	s_addc_u32 s5, s15, 0
	v_add_u32_e32 v5, s33, v1
	s_bfe_u32 s6, s56, 0x10006
	v_lshlrev_b32_e32 v2, 3, v6
	v_mov_b32_e32 v3, v0
	v_lshlrev_b32_e32 v1, 3, v1
	s_lshr_b32 s27, s56, 7
	s_lshl_b32 s16, s6, 6
	v_cmp_eq_u32_e32 vcc, 0, v6
	v_and_b32_e32 v162, 56, v1
	v_lshlrev_b32_e32 v9, 4, v6
	v_lshlrev_b32_e32 v181, 2, v6
	v_lshl_add_u64 v[6:7], s[14:15], 0, v[2:3]
	s_mov_b64 s[14:15], 0x1c77000
	v_lshlrev_b32_e32 v4, 1, v162
	s_bitcmp1_b32 s56, 6
	v_lshl_add_u64 v[164:165], v[6:7], 0, s[14:15]
	v_ashrrev_i32_e32 v182, 3, v5
	v_add_u32_e32 v3, 0x200, v5
	v_mul_u32_u24_e32 v7, 0x108, v8
	v_mov_b32_e32 v5, v0
	v_add_u32_e32 v1, 0, v4
	s_cselect_b64 s[10:11], -1, 0
	s_cmp_eq_u32 s6, 0
	v_ashrrev_i32_e32 v183, 3, v3
	s_movk_i32 s6, 0x90
	v_lshl_add_u64 v[166:167], s[4:5], 0, v[4:5]
	v_add3_u32 v4, v7, v2, 0
	v_mul_lo_u32 v184, v182, s6
	v_mul_lo_u32 v186, v183, s6
	v_add_u32_e32 v187, 0x4800, v4
	v_mul_u32_u24_e32 v4, 0x90, v8
	v_lshl_add_u32 v3, v182, 1, 0
	v_mul_u32_u24_e32 v185, 0x108, v162
	v_lshl_add_u32 v6, v183, 1, 0
	v_add3_u32 v188, v4, v9, 0
	v_sub_u32_e32 v4, v181, v8
	v_add_u32_e32 v190, v1, v184
	v_add_u32_e32 v192, v1, v186
	v_mbcnt_lo_u32_b32 v1, -1, 0
	s_mov_b32 s7, 0
	v_cndmask_b32_e64 v163, 0, 1.0, vcc
	s_cselect_b64 s[12:13], -1, 0
	v_or_b32_e32 v180, s16, v8
	v_subrev_u32_e32 v189, s16, v4
	s_movk_i32 s30, 0xe00
	v_mov_b64_e32 v[168:169], s[4:5]
	v_lshlrev_b32_e32 v170, 1, v2
	v_mov_b32_e32 v171, v0
	v_lshlrev_b32_e32 v172, 1, v162
	v_mov_b32_e32 v173, v0
	v_add_u32_e32 v191, v3, v185
	v_add_u32_e32 v193, v6, v185
	s_mov_b32 s31, 0x3e38aa3b
	v_mov_b32_e32 v194, 0xf149f2ca
	v_mbcnt_hi_u32_b32 v195, -1, v1
	s_mov_b32 s34, s2
	s_branch .LBB0_456
.LBB0_455:
	v_and_b32_e32 v67, 64, v195
	v_xor_b32_e32 v66, 32, v195
	v_add_u32_e32 v67, 64, v67
	v_cmp_lt_i32_e32 vcc, v66, v67
	s_lshl_b32 s6, s35, 1
	s_add_i32 s34, s34, s24
	v_cndmask_b32_e32 v66, v195, v66, vcc
	v_lshlrev_b32_e32 v70, 2, v66
	ds_bpermute_b32 v66, v70, v196
	ds_bpermute_b32 v220, v70, v1
	s_waitcnt lgkmcnt(0)
	v_add_f32_e32 v68, v196, v66
	v_add_f32_e32 v1, v1, v220
	v_div_scale_f32 v69, s[4:5], v68, v68, 1.0
	v_rcp_f32_e32 v71, v69
	v_div_scale_f32 v72, vcc, 1.0, v68, 1.0
	v_fma_f32 v73, -v69, v71, 1.0
	v_fmac_f32_e32 v71, v73, v71
	v_mul_f32_e32 v73, v72, v71
	v_fma_f32 v74, -v69, v73, v72
	v_fmac_f32_e32 v73, v74, v71
	v_fma_f32 v69, -v69, v73, v72
	v_div_fmas_f32 v69, v69, v71, v73
	v_div_fixup_f32 v71, v69, v68, 1.0
	v_div_scale_f32 v224, s[4:5], v1, v1, 1.0
	v_rcp_f32_e32 v225, v224
	v_div_scale_f32 v221, vcc, 1.0, v1, 1.0
	v_fma_f32 v223, -v224, v225, 1.0
	v_fmac_f32_e32 v225, v223, v225
	v_mul_f32_e32 v222, v221, v225
	v_fma_f32 v223, -v224, v222, v221
	v_fmac_f32_e32 v222, v223, v225
	v_fma_f32 v221, -v224, v222, v221
	v_div_fmas_f32 v221, v221, v225, v222
	v_div_fixup_f32 v1, v221, v1, 1.0
	s_lshl_b32 s20, s56, 7
	v_and_b32_e32 v232, 31, v195
	v_lshrrev_b32_e32 v233, 5, v195
	v_and_b32_e32 v234, 7, v232
	v_xor_b32_e32 v234, v234, v233
	v_lshlrev_b32_e32 v234, 4, v234
	v_lshl_add_u32 v234, v232, 7, v234
	v_add_u32_e32 v234, s20, v234
	v_xor_b32_e32 v235, 32, v234
	v_xor_b32_e32 v236, 64, v234
	v_xor_b32_e32 v237, 0x60, v234
	v_lshrrev_b32_e32 v238, 3, v195
	v_and_b32_e32 v239, 7, v195
	v_xor_b32_e32 v240, v239, v238
	v_lshlrev_b32_e32 v240, 4, v240
	v_lshl_add_u32 v240, v238, 7, v240
	v_add_u32_e32 v240, s20, v240
	v_and_b32_e32 v241, -32, v176
	v_or_b32_e32 v241, v241, v238
	v_lshlrev_b32_e32 v241, 10, v241
	v_lshl_add_u32 v241, v239, 4, v241
	v_add_u32_e32 v241, s6, v241
	v_readfirstlane_b32 s28, v168
	v_readfirstlane_b32 s29, v169
	s_sub_u32 s28, s28, 0x8000000
	s_subb_u32 s29, s29, 0
	v_mul_f32_e32 v34, v34, v71
	v_mul_f32_e32 v35, v35, v71
	v_mul_f32_e32 v36, v36, v71
	v_mul_f32_e32 v37, v37, v71
	v_mul_f32_e32 v38, v38, v71
	v_mul_f32_e32 v39, v39, v71
	v_mul_f32_e32 v40, v40, v71
	v_mul_f32_e32 v41, v41, v71
	v_cvt_pk_bf16_f32 v34, v34, v35
	v_cvt_pk_bf16_f32 v35, v36, v37
	v_cvt_pk_bf16_f32 v36, v38, v39
	v_cvt_pk_bf16_f32 v37, v40, v41
	s_nop 1
	v_permlane32_swap_b32_e32 v34, v36
	v_permlane32_swap_b32_e32 v35, v37
	ds_write_b128 v236, v[34:37]
	v_mul_f32_e32 v42, v42, v71
	v_mul_f32_e32 v43, v43, v71
	v_mul_f32_e32 v44, v44, v71
	v_mul_f32_e32 v45, v45, v71
	v_mul_f32_e32 v46, v46, v71
	v_mul_f32_e32 v47, v47, v71
	v_mul_f32_e32 v48, v48, v71
	v_mul_f32_e32 v49, v49, v71
	v_cvt_pk_bf16_f32 v42, v42, v43
	v_cvt_pk_bf16_f32 v43, v44, v45
	v_cvt_pk_bf16_f32 v44, v46, v47
	v_cvt_pk_bf16_f32 v45, v48, v49
	s_nop 1
	v_permlane32_swap_b32_e32 v42, v44
	v_permlane32_swap_b32_e32 v43, v45
	ds_write_b128 v237, v[42:45]
	v_mul_f32_e32 v50, v50, v71
	v_mul_f32_e32 v51, v51, v71
	v_mul_f32_e32 v52, v52, v71
	v_mul_f32_e32 v53, v53, v71
	v_mul_f32_e32 v54, v54, v71
	v_mul_f32_e32 v55, v55, v71
	v_mul_f32_e32 v56, v56, v71
	v_mul_f32_e32 v57, v57, v71
	v_cvt_pk_bf16_f32 v50, v50, v51
	v_cvt_pk_bf16_f32 v51, v52, v53
	v_cvt_pk_bf16_f32 v52, v54, v55
	v_cvt_pk_bf16_f32 v53, v56, v57
	s_nop 1
	v_permlane32_swap_b32_e32 v50, v52
	v_permlane32_swap_b32_e32 v51, v53
	ds_write_b128 v234, v[50:53]
	v_mul_f32_e32 v58, v58, v71
	v_mul_f32_e32 v59, v59, v71
	v_mul_f32_e32 v60, v60, v71
	v_mul_f32_e32 v61, v61, v71
	v_mul_f32_e32 v62, v62, v71
; __device__ __forceinline__ unsigned cvt_pk_bf16(float lo, float hi) { unsigned r; asm("v_cvt_pk_bf16_f32 %0, %1, %2" : "=v"(r) : "v"(lo), "v"(hi)); return r; }
; __device__ __forceinline__ void attn_mfma(PP p, unsigned char* shm, int wv) {
;     ...
;     for (int item = blockIdx.x; item < 512; item += gridDim.x) {
;         const int hk = item & 1, qb = (item >> 1) & 127, b = item >> 8;
;         const int g = wave >> 1, qh = wave & 1, hq = hk * 4 + g;
;         const int qrow0 = b * S + 128 * qb + 64 * qh;
;         bf16x8 qf[2][4];
; #pragma unroll
;         for (int qi = 0; qi < 2; ++qi)
; #pragma unroll
;             for (int st = 0; st < 4; ++st) qf[qi][st] = *(const bf16x8*)(proj + (size_t)(qrow0 + 32 * qi + l31) * DIN + 1024 + 64 * hq + 16 * st + 8 * hl);
;         const float sink2 = p->attn_sink[hq] * L2E;
;         float mrun[2] = {sink2, sink2};
;         float lrun[2] = {hl == 0 ? 1.f : 0.f, hl == 0 ? 1.f : 0.f};
;         f32x16 oacc[2][2];
; #pragma unroll
;         for (int a = 0; a < 2; ++a)
; #pragma unroll
;             for (int c = 0; c < 2; ++c)
; #pragma unroll
;                 for (int i = 0; i < 16; ++i) oacc[a][c][i] = 0.f;
;         u32x4 kreg[2], vreg[2];
;         int ci = (qb == 0) ? 1 : 0;
;     ...
; #pragma unroll
;         for (int qi = 0; qi < 2; ++qi) {
;             const float lt = lrun[qi] + __shfl_xor(lrun[qi], 32);
;             const float inv = 1.0f / lt;
;             bf16_t* orow = att + (size_t)(qrow0 + 32 * qi + l31) * 512 + hq * 64;
; #pragma unroll
;             for (int db = 0; db < 2; ++db)
; #pragma unroll
;                 for (int g4 = 0; g4 < 4; ++g4) {
;                     u32x2 w; w.x = cvt_pk_bf16(oacc[db][qi][4 * g4] * inv, oacc[db][qi][4 * g4 + 1] * inv); w.y = cvt_pk_bf16(oacc[db][qi][4 * g4 + 2] * inv, oacc[db][qi][4 * g4 + 3] * inv);
;                     *(u32x2*)(orow + 32 * db + 8 * g4 + 4 * hl) = w;
;                 }
;         }
	v_mul_f32_e32 v63, v63, v71
	v_mul_f32_e32 v64, v64, v71
	v_mul_f32_e32 v65, v65, v71
	v_cvt_pk_bf16_f32 v58, v58, v59
	v_cvt_pk_bf16_f32 v59, v60, v61
	v_cvt_pk_bf16_f32 v60, v62, v63
	v_cvt_pk_bf16_f32 v61, v64, v65
	s_nop 1
	v_permlane32_swap_b32_e32 v58, v60
	v_permlane32_swap_b32_e32 v59, v61
	ds_write_b128 v235, v[58:61]
	v_mul_f32_e32 v18, v18, v1
	v_mul_f32_e32 v19, v19, v1
	v_mul_f32_e32 v20, v20, v1
	v_mul_f32_e32 v21, v21, v1
	v_mul_f32_e32 v22, v22, v1
	v_mul_f32_e32 v23, v23, v1
	v_mul_f32_e32 v24, v24, v1
	v_mul_f32_e32 v25, v25, v1
	v_cvt_pk_bf16_f32 v18, v18, v19
	v_cvt_pk_bf16_f32 v19, v20, v21
	v_cvt_pk_bf16_f32 v20, v22, v23
	v_cvt_pk_bf16_f32 v21, v24, v25
	s_nop 1
	v_permlane32_swap_b32_e32 v18, v20
	v_permlane32_swap_b32_e32 v19, v21
	ds_write_b128 v234, v[18:21] offset:4096
	v_mul_f32_e32 v26, v26, v1
	v_mul_f32_e32 v27, v27, v1
	v_mul_f32_e32 v28, v28, v1
	v_mul_f32_e32 v29, v29, v1
	v_mul_f32_e32 v30, v30, v1
	v_mul_f32_e32 v31, v31, v1
	v_mul_f32_e32 v32, v32, v1
	v_mul_f32_e32 v33, v33, v1
	v_cvt_pk_bf16_f32 v26, v26, v27
	v_cvt_pk_bf16_f32 v27, v28, v29
	v_cvt_pk_bf16_f32 v28, v30, v31
	v_cvt_pk_bf16_f32 v29, v32, v33
	s_nop 1
	v_permlane32_swap_b32_e32 v26, v28
	v_permlane32_swap_b32_e32 v27, v29
	ds_write_b128 v235, v[26:29] offset:4096
	v_mul_f32_e32 v2, v2, v1
	v_mul_f32_e32 v3, v3, v1
	v_mul_f32_e32 v4, v4, v1
	v_mul_f32_e32 v5, v5, v1
	v_mul_f32_e32 v6, v6, v1
	v_mul_f32_e32 v7, v7, v1
	v_mul_f32_e32 v8, v8, v1
	v_mul_f32_e32 v9, v9, v1
	v_cvt_pk_bf16_f32 v2, v2, v3
	v_cvt_pk_bf16_f32 v3, v4, v5
	v_cvt_pk_bf16_f32 v4, v6, v7
	v_cvt_pk_bf16_f32 v5, v8, v9
	s_nop 1
	v_permlane32_swap_b32_e32 v2, v4
	v_permlane32_swap_b32_e32 v3, v5
	ds_write_b128 v236, v[2:5] offset:4096
	v_mul_f32_e32 v10, v10, v1
	v_mul_f32_e32 v11, v11, v1
	v_mul_f32_e32 v12, v12, v1
	v_mul_f32_e32 v13, v13, v1
	v_mul_f32_e32 v14, v14, v1
	v_mul_f32_e32 v15, v15, v1
	v_mul_f32_e32 v16, v16, v1
	v_mul_f32_e32 v17, v17, v1
	v_cvt_pk_bf16_f32 v10, v10, v11
	v_cvt_pk_bf16_f32 v11, v12, v13
	v_cvt_pk_bf16_f32 v12, v14, v15
	v_cvt_pk_bf16_f32 v13, v16, v17
	s_nop 1
	v_permlane32_swap_b32_e32 v10, v12
	v_permlane32_swap_b32_e32 v11, v13
	ds_write_b128 v237, v[10:13] offset:4096
	ds_read_b128 v[66:69], v240
	ds_read_b128 v[70:73], v240 offset:1024
	ds_read_b128 v[74:77], v240 offset:2048
	ds_read_b128 v[78:81], v240 offset:3072
	ds_read_b128 v[130:133], v240 offset:4096
	ds_read_b128 v[134:137], v240 offset:5120
	ds_read_b128 v[138:141], v240 offset:6144
	ds_read_b128 v[142:145], v240 offset:7168
	v_add_u32_e32 v242, 0x2000, v241
	v_add_u32_e32 v243, 0x4000, v241
	v_add_u32_e32 v244, 0x6000, v241
	v_add_u32_e32 v245, 0x8000, v241
	v_add_u32_e32 v246, 0xa000, v241
	v_add_u32_e32 v247, 0xc000, v241
	v_add_u32_e32 v248, 0xe000, v241
	s_waitcnt lgkmcnt(7)
	global_store_dwordx4 v241, v[66:69], s[28:29]
	s_waitcnt lgkmcnt(6)
	global_store_dwordx4 v242, v[70:73], s[28:29]
	s_waitcnt lgkmcnt(5)
	global_store_dwordx4 v243, v[74:77], s[28:29]
	s_waitcnt lgkmcnt(4)
	global_store_dwordx4 v244, v[78:81], s[28:29]
	s_waitcnt lgkmcnt(3)
	global_store_dwordx4 v245, v[130:133], s[28:29]
	s_waitcnt lgkmcnt(2)
	global_store_dwordx4 v246, v[134:137], s[28:29]
	s_waitcnt lgkmcnt(1)
	global_store_dwordx4 v247, v[138:141], s[28:29]
	s_waitcnt lgkmcnt(0)
	global_store_dwordx4 v248, v[142:145], s[28:29]
	s_cmpk_gt_i32 s34, 0x1ff
	s_cbranch_scc1 .LBB0_489
.LBB0_456:
	s_and_b32 s14, s34, 1
	s_lshl_b32 s4, s14, 2
	s_add_i32 s16, s4, s27
	s_lshl_b32 s4, s34, 6
	s_bfe_u32 s15, s34, 0x70001
	s_and_b32 s17, s4, 0xffffc000
	s_lshl_b32 s18, s15, 7
	v_or_b32_e32 v1, s17, v180
	v_or_b32_e32 v176, s18, v1
	v_mad_i64_i32 v[2:3], s[4:5], v176, s30, v[168:169]
	s_lshl_b32 s6, s16, 7
	v_or_b32_e32 v174, 32, v176
	v_lshl_add_u64 v[18:19], v[2:3], 0, s[6:7]
	v_mad_i64_i32 v[2:3], s[4:5], v174, s30, v[168:169]
	s_lshl_b32 s4, s16, 2
	v_sub_co_u32_e64 v24, vcc, s15, 1
	v_lshl_add_u64 v[20:21], v[2:3], 0, s[6:7]
	v_mov_b32_e32 v1, s4
	v_addc_co_u32_e64 v2, s[4:5], 0, v24, vcc
	v_lshlrev_b32_e32 v2, 7, v2
	v_add_u32_e32 v12, s17, v2
	v_add_u32_e32 v2, v12, v182
	v_mad_i64_i32 v[2:3], s[4:5], v2, s30, v[168:169]
	s_lshl_b32 s6, s14, 7
	v_lshl_add_u64 v[2:3], v[2:3], 0, s[6:7]
	v_lshl_add_u64 v[10:11], v[2:3], 0, v[172:173]
	global_load_dword v1, v1, s[8:9]
	s_nop 0
	s_cmp_eq_u32 s97, 1
	s_cbranch_scc1 .Lattn_pf_sk1
	global_load_dwordx4 v[2:5], v[10:11], off offset:3072
	global_load_dwordx4 v[6:9], v[10:11], off offset:3328
; __device__ __forceinline__ void attn_mfma(PP p, unsigned char* shm, int wv) {
;     ...
;         bf16x8 qf[2][4];
; #pragma unroll
;         for (int qi = 0; qi < 2; ++qi)
; #pragma unroll
;             for (int st = 0; st < 4; ++st) qf[qi][st] = *(const bf16x8*)(proj + (size_t)(qrow0 + 32 * qi + l31) * DIN + 1024 + 64 * hq + 16 * st + 8 * hl);
;         const float sink2 = p->attn_sink[hq] * L2E;
;         float mrun[2] = {sink2, sink2};
;         float lrun[2] = {hl == 0 ? 1.f : 0.f, hl == 0 ? 1.f : 0.f};
;         f32x16 oacc[2][2];
; #pragma unroll
;         for (int a = 0; a < 2; ++a)
; #pragma unroll
;             for (int c = 0; c < 2; ++c)
; #pragma unroll
;                 for (int i = 0; i < 16; ++i) oacc[a][c][i] = 0.f;
;         u32x4 kreg[2], vreg[2];
;         int ci = (qb == 0) ? 1 : 0;
;     ...
;         ATT_GLOAD(ci);
;         __syncthreads();
;         ATT_STAGE(0);
;         { const int c1 = ATT_NEXT(ci); if (c1 < 5) ATT_GLOAD(c1); }
;         __syncthreads();
.Lattn_pf_sk1:
	v_add_u32_e32 v10, v12, v183
	v_mad_i64_i32 v[10:11], s[4:5], v10, s30, v[168:169]
	v_lshl_add_u64 v[10:11], v[10:11], 0, s[6:7]
	s_lshl_b32 s35, s16, 6
	v_lshl_add_u64 v[22:23], v[10:11], 0, v[172:173]
	v_lshl_add_u64 v[18:19], v[18:19], 0, v[170:171]
	s_and_b64 s[4:5], vcc, exec
	s_cselect_b32 s4, 2, 1
	s_cmp_eq_u32 s97, 1
	s_cbranch_scc1 .Lattn_pf_sk2
	global_load_dwordx4 v[10:13], v[22:23], off offset:3072
	global_load_dwordx4 v[14:17], v[22:23], off offset:3328
.Lattn_pf_sk2:
	global_load_dwordx4 v[82:85], v[18:19], off offset:2048
	global_load_dwordx4 v[86:89], v[18:19], off offset:2080
	global_load_dwordx4 v[90:93], v[18:19], off offset:2112
	global_load_dwordx4 v[94:97], v[18:19], off offset:2144
	v_lshl_add_u64 v[18:19], v[20:21], 0, v[170:171]
	global_load_dwordx4 v[98:101], v[18:19], off offset:2048
	global_load_dwordx4 v[102:105], v[18:19], off offset:2080
	global_load_dwordx4 v[106:109], v[18:19], off offset:2112
	global_load_dwordx4 v[110:113], v[18:19], off offset:2144
	v_add_u32_e32 v18, s4, v24
	v_lshlrev_b32_e32 v18, 7, v18
	v_add_u32_e32 v20, s17, v18
	v_add_u32_e32 v18, v20, v182
	v_mad_i64_i32 v[18:19], s[4:5], v18, s30, v[168:169]
	v_lshl_add_u64 v[18:19], v[18:19], 0, s[6:7]
	v_lshl_add_u64 v[18:19], v[18:19], 0, v[172:173]
	s_waitcnt vmcnt(63) expcnt(7) lgkmcnt(15)
	s_barrier
	global_load_dwordx4 v[114:117], v[18:19], off offset:3072
	global_load_dwordx4 v[118:121], v[18:19], off offset:3328
	v_add_u32_e32 v18, v20, v183
	v_mad_i64_i32 v[18:19], s[4:5], v18, s30, v[168:169]
	v_lshl_add_u64 v[18:19], v[18:19], 0, s[6:7]
	v_lshl_add_u64 v[18:19], v[18:19], 0, v[172:173]
	global_load_dwordx4 v[122:125], v[18:19], off offset:3072
	global_load_dwordx4 v[126:129], v[18:19], off offset:3328
	v_cndmask_b32_e64 v25, 0, 1, vcc
	s_cmpk_eq_i32 s15, 0x7f
	v_readfirstlane_b32 s38, v25
	s_cselect_b64 s[4:5], -1, 0
	s_and_b32 s36, s34, 0xffffff00
	s_or_b32 s37, s18, s17
	v_ashrrev_i32_e32 v177, 31, v176
	v_ashrrev_i32_e32 v175, 31, v174
	s_addk_i32 s36, 0x7e80
	s_addk_i32 s37, 0x80
	v_lshl_add_u64 v[178:179], v[166:167], 0, s[6:7]
	v_mov_b32_e32 v196, v163
	s_mov_b32 s6, 0
	s_waitcnt vmcnt(15)
	s_cmp_eq_u32 s97, 1
	s_cbranch_scc0 .Lattn_pf_norb
	s_mov_b32 s97, 0
	s_lshl_b32 s98, s33, 6
	s_add_i32 s98, s98, 0x12000
	v_lshlrev_b32_e32 v66, 4, v195
	v_add_u32_e32 v66, s98, v66
	ds_read_b128 v[2:5], v66
	ds_read_b128 v[6:9], v66 offset:1024
	ds_read_b128 v[10:13], v66 offset:2048
	ds_read_b128 v[14:17], v66 offset:3072
	s_waitcnt lgkmcnt(0)
.Lattn_pf_norb:
	ds_write_b128 v190, v[2:5]
	s_waitcnt vmcnt(14)
	ds_write_b16 v191, v6 offset:18432
	ds_write_b16_d16_hi v191, v6 offset:18696
	ds_write_b16 v191, v7 offset:18960
	ds_write_b16_d16_hi v191, v7 offset:19224
	ds_write_b16 v191, v8 offset:19488
	ds_write_b16_d16_hi v191, v8 offset:19752
	ds_write_b16 v191, v9 offset:20016
	ds_write_b16_d16_hi v191, v9 offset:20280
	s_waitcnt vmcnt(13)
	ds_write_b128 v192, v[10:13]
	s_waitcnt vmcnt(12)
	ds_write_b16 v193, v14 offset:18432
	ds_write_b16_d16_hi v193, v14 offset:18696
	ds_write_b16 v193, v15 offset:18960
	ds_write_b16_d16_hi v193, v15 offset:19224
	ds_write_b16 v193, v16 offset:19488
	ds_write_b16_d16_hi v193, v16 offset:19752
	ds_write_b16 v193, v17 offset:20016
	ds_write_b16_d16_hi v193, v17 offset:20280
	v_mov_b32_e32 v14, v0
	v_mov_b32_e32 v15, v0
	v_mul_f32_e32 v197, 0x3fb8aa3b, v1
	v_mov_b32_e32 v1, v0
	v_mov_b32_e32 v2, v0
	v_mov_b32_e32 v3, v0
	v_mov_b32_e32 v4, v0
	v_mov_b32_e32 v5, v0
	v_mov_b32_e32 v6, v0
	v_mov_b32_e32 v7, v0
	v_mov_b32_e32 v8, v0
	v_mov_b32_e32 v9, v0
	v_mov_b32_e32 v10, v0
	v_mov_b32_e32 v11, v0
	v_mov_b32_e32 v12, v0
	v_mov_b32_e32 v13, v0
	v_mov_b64_e32 v[64:65], v[14:15]
	v_mov_b64_e32 v[32:33], v[14:15]
	v_mov_b64_e32 v[48:49], v[14:15]
	v_mov_b64_e32 v[62:63], v[12:13]
	v_mov_b64_e32 v[60:61], v[10:11]
	v_mov_b64_e32 v[58:59], v[8:9]
	v_mov_b64_e32 v[56:57], v[6:7]
	v_mov_b64_e32 v[54:55], v[4:5]
	v_mov_b64_e32 v[52:53], v[2:3]
	v_mov_b64_e32 v[50:51], v[0:1]
	v_mov_b64_e32 v[30:31], v[12:13]
	v_mov_b64_e32 v[28:29], v[10:11]
	v_mov_b64_e32 v[26:27], v[8:9]
	v_mov_b64_e32 v[24:25], v[6:7]
	v_mov_b64_e32 v[22:23], v[4:5]
	v_mov_b64_e32 v[20:21], v[2:3]
	v_mov_b64_e32 v[18:19], v[0:1]
	v_mov_b64_e32 v[46:47], v[12:13]
	v_mov_b64_e32 v[44:45], v[10:11]
	v_mov_b64_e32 v[42:43], v[8:9]
	v_mov_b64_e32 v[40:41], v[6:7]
	v_mov_b64_e32 v[38:39], v[4:5]
	v_mov_b64_e32 v[36:37], v[2:3]
	v_mov_b64_e32 v[34:35], v[0:1]
	v_mov_b64_e32 v[16:17], v[14:15]
	v_mov_b64_e32 v[14:15], v[12:13]
	v_mov_b64_e32 v[12:13], v[10:11]
	v_mov_b64_e32 v[10:11], v[8:9]
	v_mov_b64_e32 v[8:9], v[6:7]
	v_mov_b64_e32 v[6:7], v[4:5]
	v_mov_b64_e32 v[4:5], v[2:3]
	v_mov_b64_e32 v[2:3], v[0:1]
	v_mov_b32_e32 v1, v163
	v_mov_b32_e32 v198, v197
	s_waitcnt lgkmcnt(0)
	s_barrier

; __device__ __forceinline__ void attn_mfma(PP p, unsigned char* shm, int wv) {
;     ...
;         while (ci < 5) {
;             const int cn = ATT_NEXT(ci);
;             if (cn < 5) { ATT_STAGE(par ^ 1); const int c2 = ATT_NEXT(cn); if (c2 < 5) ATT_GLOAD(c2); }
;             const bf16_t* Ks = (const bf16_t*)(shm + par * 36864);
;             const bf16_t* Vt = (const bf16_t*)(shm + par * 36864 + 18432);
;             const int kt_lo = (ci == 0 && qh == 1) ? 2 : 0, kt_hi = (ci == 2 && qh == 0) ? 2 : 4;
; #pragma unroll 1
;             for (int kt = kt_lo; kt < kt_hi; ++kt) {
.LBB0_460:
	s_cmp_eq_u32 s38, 0
	s_cselect_b64 s[16:17], -1, 0
	s_cmp_lg_u32 s38, 0
	s_cselect_b64 s[18:19], -1, 0
	s_and_b64 s[20:21], s[10:11], s[16:17]
	s_and_b64 s[20:21], s[20:21], exec
	s_cselect_b32 s40, 2, 0
	s_cmp_eq_u32 s38, 2
	s_cselect_b64 s[20:21], -1, 0
	s_and_b64 s[20:21], s[12:13], s[20:21]
	s_and_b64 s[20:21], s[20:21], exec
	s_cselect_b32 s41, 2, 4
	s_cmp_ge_u32 s40, s41
	s_cbranch_scc1 .LBB0_487
	s_mul_i32 s20, s6, 0x9000
	s_lshl_b32 s21, s40, 6
	s_or_b32 s21, s20, s21
	v_add_u32_e32 v199, s21, v187
	s_mul_i32 s21, s40, 0x1200
	s_add_i32 s20, s20, s21
	v_add_u32_e32 v200, s20, v188
	v_lshl_add_u32 v201, s40, 5, v189
	s_cmp_eq_u32 s38, 0
	s_cbranch_scc1 .Lattn_p_entry_m0
	s_cmp_eq_u32 s38, 2
	s_cbranch_scc1 .Lattn_p_entry_m2
	s_cmp_lg_u32 s38, 4
	s_cbranch_scc1 .Lattn_p_entry_u
	s_add_i32 s98, s34, s24
	s_cmpk_gt_i32 s98, 0x1ff
	s_cbranch_scc1 .Lattn_p_entry_u
	s_bfe_u32 s100, s98, 0x70001
	s_add_i32 s100, s100, -1
	s_max_i32 s100, s100, 0
	s_lshl_b32 s100, s100, 7
	s_lshl_b32 s101, s98, 6
	s_and_b32 s101, s101, 0xffffc000
	s_add_i32 s100, s100, s101
	s_and_b32 s98, s98, 1
	s_lshl_b32 s98, s98, 7
	s_addk_i32 s98, 0xc00
	s_mov_b32 s99, 0
	v_add_u32_e32 v220, s100, v182
	v_add_u32_e32 v221, s100, v183
	v_mad_i64_i32 v[222:223], s[100:101], v220, s30, v[168:169]
	v_mad_i64_i32 v[226:227], s[100:101], v221, s30, v[168:169]
	v_lshl_add_u64 v[222:223], v[222:223], 0, v[172:173]
	v_lshl_add_u64 v[226:227], v[226:227], 0, v[172:173]
	v_lshl_add_u64 v[222:223], v[222:223], 0, s[98:99]
	v_lshl_add_u64 v[226:227], v[226:227], 0, s[98:99]
	s_movk_i32 s98, 0x100
	v_lshl_add_u64 v[224:225], v[222:223], 0, s[98:99]
	v_lshl_add_u64 v[228:229], v[226:227], 0, s[98:99]
	s_lshl_b32 s101, s33, 6
	s_add_i32 s101, s101, 0x12000
	s_mov_b32 m0, s101
	s_nop 0
	global_load_lds_dwordx4 v[222:223], off
	s_add_i32 m0, s101, 0x400
	s_nop 0
	global_load_lds_dwordx4 v[224:225], off
	s_add_i32 m0, s101, 0x800
	s_nop 0
	global_load_lds_dwordx4 v[226:227], off
	s_add_i32 m0, s101, 0xc00
	s_nop 0
	global_load_lds_dwordx4 v[228:229], off
	s_mov_b32 s97, 1
	s_branch .Lattn_p_entry_u
